# same local P10-P11 seam, now guarded on a 256-workgroup grid with the unit remap done at decode time (other grid sizes take the baseline path)
# speedup vs baseline: 1.0014x; 1.0014x over previous
; __device__ __forceinline__ unsigned xb_ld(unsigned* p)              { return __hip_atomic_load(p, __ATOMIC_RELAXED, __HIP_MEMORY_SCOPE_AGENT); }
; __device__ __forceinline__ unsigned xb_add(unsigned* p, unsigned v) { return __hip_atomic_fetch_add(p, v, __ATOMIC_RELAXED, __HIP_MEMORY_SCOPE_AGENT); }
; #define XB_SPIN(cond, bar) do { unsigned _sp = 0; while (cond) { __builtin_amdgcn_s_sleep(1); \
;     if ((++_sp & 255u) == 0u) { if (xb_ld(&(bar)[XB_TMO])) break; if (_sp > XB_SPIN_CAP) { atomicAdd(&(bar)[XB_TMO], 1u); break; } } } } while (0)
; __device__ __forceinline__ void xcd_barrier(const XcdBarrier& b) {
;     asm volatile("s_waitcnt vmcnt(0)" ::: "memory");
;     __syncthreads();
;     if (threadIdx.x == 0) {
;         unsigned* bar = b.bar;
;         __builtin_amdgcn_s_waitcnt(0);
;         unsigned nloc = b.st[0], nx = b.st[1];
;         if (nloc == 0u) { xcd_barrier_complete(bar, b.x, nloc, nx); b.st[0] = nloc; b.st[1] = nx; }
;         const unsigned old = xb_add(&bar[XB_XSUB(b.x)], 1u);
;         const unsigned gen = old / nloc;
;         if (old + 1u == (gen + 1u) * nloc) {
;             __builtin_amdgcn_fence(__ATOMIC_RELEASE, "agent");
;             asm volatile("s_waitcnt vmcnt(0)" ::: "memory");
;             const unsigned og = xb_add(&bar[XB_TOP], 1u);
;             const unsigned tg = og / nx;
;             if (og + 1u == (tg + 1u) * nx) xb_add(&bar[XB_TOPGEN], 1u);
;             else XB_SPIN(xb_ld(&bar[XB_TOPGEN]) == tg, bar);
;             __builtin_amdgcn_fence(__ATOMIC_ACQUIRE, "agent");
;             xb_add(&bar[XB_XGEN(b.x)], 1u);
;             asm volatile("s_waitcnt vmcnt(0)" ::: "memory");
;         } else {
;             XB_SPIN(xb_ld(&bar[XB_XGEN(b.x)]) == gen, bar);
;             __builtin_amdgcn_fence(__ATOMIC_ACQUIRE, "agent");
;             asm volatile("s_waitcnt vmcnt(0)" ::: "memory");
;         }
;     }
;     __syncthreads();
; }
.LBB0_786:
	s_cmp_gt_i32 s11, 11
	s_cselect_b64 s[0:1], -1, 0
	s_and_b64 s[2:3], s[4:5], s[0:1]
	s_andn2_b64 vcc, exec, s[2:3]
	s_cbranch_vccnz .LBB0_840
	s_waitcnt vmcnt(0)
	s_waitcnt vmcnt(0) lgkmcnt(0)
	s_barrier
	s_cmp_eq_u32 s9, 0x100
	s_cbranch_scc0 .Lp11_glob
	buffer_inv sc1
	s_waitcnt vmcnt(0)
	s_branch .LBB0_840
.Lp11_glob:
	s_and_saveexec_b64 s[2:3], s[6:7]
	s_cbranch_execz .LBB0_839
	s_add_i32 s4, 0, 0x20000
	v_mov_b32_e32 v0, s4
	s_waitcnt vmcnt(0) expcnt(0) lgkmcnt(0)
	ds_read_b32 v2, v0
	s_add_i32 s4, 0, 0x20004
	v_mov_b32_e32 v0, s4
	ds_read_b32 v0, v0
	s_waitcnt lgkmcnt(1)
	v_cmp_ne_u32_e32 vcc, 0, v2
	s_cbranch_vccnz .LBB0_803
	s_load_dwordx2 s[14:15], s[92:93], 0x4
	s_add_u32 s4, s26, 0x1000
	s_addc_u32 s5, s27, 0
	s_add_u32 s12, s26, 0x1100
	s_addc_u32 s13, s27, 0
	s_waitcnt lgkmcnt(0)
	s_mul_i32 s28, s14, s9
	s_add_u32 s14, s26, 0x1200
	s_mul_i32 s28, s28, s15
	s_addc_u32 s15, s27, 0
	s_add_u32 s16, s26, 0x1300
	s_addc_u32 s17, s27, 0
	s_mov_b32 s29, 1
	v_mov_b32_e32 v16, 0
	s_branch .LBB0_791

;     ...
;   PLOAD(0); asm volatile("s_waitcnt vmcnt(0)" ::: "memory"); PWRITE(0); __syncthreads();
;   qkt(pA0, pA1, KSUB(0, 0), qr, r32, hi); partialSM(pA0, pA1, m_reg, mnA, alA);
; __global__ void __launch_bounds__(NWAVES * 64, 2) mk_fwd(Args args) {
;     ...
;         for (int u = vcu; u < 512; u += G) {
;             const int qb = u >> 2, h = u & 3; const size_t rowq = (size_t)qb * 256; const int b = (int)(rowq / SEQ);
;             const att::bf16* kv = (const att::bf16*)KVM + (size_t)b * MEMT * (2 * MEMW);
;             att::attn_unit<0>((const att::bf16*)QM + rowq * MEMW + h * 128, MEMW, kv + h * 128, kv + MEMW + h * 128, 2 * MEMW,
.LBB0_843:
	s_and_b32 s4, s70, 0xff
	s_lshr_b32 s5, s4, 4
	s_lshl_b32 s5, s5, 5
	s_and_b32 s2, s4, 7
	s_lshl_b32 s2, s2, 2
	s_add_i32 s5, s5, s2
	s_bfe_u32 s2, s4, 0x10003
	s_lshl_b32 s2, s2, 1
	s_add_i32 s5, s5, s2
	s_lshr_b32 s2, s70, 8
	s_add_i32 s5, s5, s2
	s_cmp_eq_u32 s9, 0x100
	s_cselect_b32 s5, s5, s70
	s_lshl_b32 s34, s5, 7
	s_ashr_i32 s4, s5, 2
	s_ashr_i32 s5, s4, 31
	s_lshl_b64 s[0:1], s[4:5], 13
	s_and_b32 s0, s0, 0xfff80000
	s_add_u32 s14, s18, s0
	s_addc_u32 s15, s19, s1
	s_lshl_b64 s[0:1], s[4:5], 18
	s_add_u32 s0, s20, s0
	s_addc_u32 s1, s21, s1
	s_and_b32 s2, s34, 0x180
	s_lshl_b32 s50, s2, 1
	v_mov_b32_e32 v42, v218
	s_add_u32 s2, s0, s50
	s_addc_u32 s3, s1, 0
	v_lshlrev_b32_e32 v44, 3, v42
	v_and_b32_e32 v0, 0x78, v44
	s_add_u32 s0, s14, s50
	v_ashrrev_i32_e32 v43, 4, v42
	v_lshlrev_b32_e32 v45, 1, v0
	s_addc_u32 s1, s15, 0
	v_lshl_or_b32 v34, v43, 11, v45
	v_mov_b32_e32 v35, v161
	v_lshl_add_u64 v[32:33], s[0:1], 0, v[34:35]
	v_add_co_u32_e32 v36, vcc, s38, v32
	global_load_dwordx4 v[0:3], v34, s[0:1] offset:1024
	s_nop 0
	v_addc_co_u32_e32 v37, vcc, 0, v33, vcc
	v_add_co_u32_e32 v38, vcc, s40, v32
	global_load_dwordx4 v[4:7], v[36:37], off offset:1024
	s_nop 0
	v_addc_co_u32_e32 v39, vcc, 0, v33, vcc
	v_add_co_u32_e32 v40, vcc, s41, v32
	global_load_dwordx4 v[8:11], v[38:39], off offset:1024
	s_nop 0
	v_addc_co_u32_e32 v41, vcc, 0, v33, vcc
	global_load_dwordx4 v[12:15], v[40:41], off offset:1024
	global_load_dwordx4 v[16:19], v34, s[0:1]
	global_load_dwordx4 v[20:23], v[36:37], off
	global_load_dwordx4 v[24:27], v[38:39], off
	global_load_dwordx4 v[28:31], v[40:41], off
	v_readfirstlane_b32 s0, v42
	s_ashr_i32 s16, s0, 1
	v_mov_b32_e32 v34, s16
	v_bfi_b32 v34, s36, v34, v42
	v_ashrrev_i32_e32 v35, 31, v34
	v_bfe_u32 v163, v42, 5, 1
	v_lshlrev_b64 v[34:35], 10, v[34:35]
	v_lshl_add_u64 v[34:35], s[2:3], 0, v[34:35]
	v_lshlrev_b32_e32 v160, 4, v163
	v_lshl_add_u64 v[34:35], v[34:35], 0, v[160:161]
	global_load_dwordx4 v[124:127], v[34:35], off
	global_load_dwordx4 v[116:119], v[34:35], off offset:32
	global_load_dwordx4 v[120:123], v[34:35], off offset:64
	global_load_dwordx4 v[112:115], v[34:35], off offset:96
	global_load_dwordx4 v[108:111], v[34:35], off offset:128
	global_load_dwordx4 v[104:107], v[34:35], off offset:160
	global_load_dwordx4 v[100:103], v[34:35], off offset:192
	global_load_dwordx4 v[96:99], v[34:35], off offset:224
	v_and_b32_e32 v37, 0xfffff0, v43
	v_lshlrev_b32_e32 v38, 1, v43
	v_lshrrev_b32_e32 v39, 1, v43
	v_and_b32_e32 v41, 3, v43
	v_and_or_b32 v37, v38, 8, v37
	v_bfe_u32 v40, v44, 5, 2
	v_and_or_b32 v38, v39, 4, v41
	v_lshrrev_b32_e32 v37, 1, v37
	v_and_b32_e32 v39, 48, v45
	v_and_b32_e32 v36, 0x70, v42
	v_lshlrev_b32_e32 v43, 8, v43
	v_or_b32_e32 v37, v37, v40
	v_lshl_or_b32 v38, v38, 6, v39
	v_and_b32_e32 v164, 31, v42
	v_lshlrev_b32_e32 v46, 4, v42
	v_bitop3_b32 v36, v45, v43, v36 bitop3:0xde
	v_lshl_or_b32 v181, v37, 9, v38
	v_add_u32_e32 v180, 0, v36
	v_add_u32_e32 v36, 0x2000, v181
	v_add_u32_e32 v37, s39, v181
	v_lshlrev_b32_e32 v43, 8, v164
	v_and_b32_e32 v44, 0x70, v46
	v_add_u32_e32 v38, s42, v181
	v_add_u32_e32 v39, s39, v36
	v_add_u32_e32 v36, s42, v36
	s_waitcnt vmcnt(0)
	v_or_b32_e32 v34, 32, v160
	v_bitop3_b32 v34, v34, v43, v44 bitop3:0xde
	v_add_u32_e32 v171, 0, v34
	v_and_b32_e32 v165, 63, v42
	v_lshlrev_b32_e32 v42, 1, v42
	s_cmp_lg_u32 s39, -1
	s_cselect_b32 s1, s39, 0
	s_waitcnt vmcnt(0)
	ds_write_b128 v37, v[0:3]
	ds_write_b128 v39, v[4:7]
	ds_write_b128 v38, v[8:11]
	ds_write_b128 v36, v[12:15]
	ds_write_b128 v180, v[16:19]
	ds_write_b128 v180, v[20:23] offset:8192
	ds_write_b128 v180, v[24:27] offset:16384
	ds_write_b128 v180, v[28:31] offset:24576
	v_bitop3_b32 v0, v160, v43, v44 bitop3:0xde
	v_add_u32_e32 v170, 0, v0
	s_waitcnt lgkmcnt(0)
	s_barrier
	ds_read_b128 v[0:3], v170
	ds_read_b128 v[4:7], v170 offset:8192
	s_waitcnt lgkmcnt(1)
	v_mfma_f32_32x32x16_bf16 v[16:31], v[0:3], v[124:127], 0
	ds_read_b128 v[34:37], v171
	ds_read_b128 v[38:41], v171 offset:8192
	s_waitcnt lgkmcnt(2)
	v_mfma_f32_32x32x16_bf16 v[0:15], v[4:7], v[124:127], 0
	s_waitcnt lgkmcnt(1)
	v_mfma_f32_32x32x16_bf16 v[16:31], v[34:37], v[116:119], v[16:31]
	v_or_b32_e32 v34, 64, v160
	v_bitop3_b32 v34, v34, v43, v44 bitop3:0xde
	v_add_u32_e32 v172, 0, v34
	s_waitcnt lgkmcnt(0)
	v_mfma_f32_32x32x16_bf16 v[0:15], v[38:41], v[116:119], v[0:15]
	ds_read_b128 v[34:37], v172
	ds_read_b128 v[38:41], v172 offset:8192
	s_waitcnt lgkmcnt(1)
	v_mfma_f32_32x32x16_bf16 v[16:31], v[34:37], v[120:123], v[16:31]
	v_or_b32_e32 v34, 0x60, v160
	v_bitop3_b32 v34, v34, v43, v44 bitop3:0xde
	v_add_u32_e32 v173, 0, v34
	s_waitcnt lgkmcnt(0)
	v_mfma_f32_32x32x16_bf16 v[0:15], v[38:41], v[120:123], v[0:15]
	ds_read_b128 v[34:37], v173
	ds_read_b128 v[38:41], v173 offset:8192
	s_waitcnt lgkmcnt(1)
	v_mfma_f32_32x32x16_bf16 v[16:31], v[34:37], v[112:115], v[16:31]
	v_or_b32_e32 v34, 0x80, v160
	v_bitop3_b32 v34, v34, v43, v44 bitop3:0xde
	v_add_u32_e32 v174, 0, v34
	s_waitcnt lgkmcnt(0)
	v_mfma_f32_32x32x16_bf16 v[0:15], v[38:41], v[112:115], v[0:15]
	ds_read_b128 v[34:37], v174
	ds_read_b128 v[38:41], v174 offset:8192
	s_waitcnt lgkmcnt(1)
	v_mfma_f32_32x32x16_bf16 v[16:31], v[34:37], v[108:111], v[16:31]
	v_or_b32_e32 v34, 0xa0, v160
	v_bitop3_b32 v34, v34, v43, v44 bitop3:0xde
	v_add_u32_e32 v175, 0, v34
	s_waitcnt lgkmcnt(0)
	v_mfma_f32_32x32x16_bf16 v[0:15], v[38:41], v[108:111], v[0:15]
	ds_read_b128 v[34:37], v175
	ds_read_b128 v[38:41], v175 offset:8192
	s_waitcnt lgkmcnt(1)
	v_mfma_f32_32x32x16_bf16 v[16:31], v[34:37], v[104:107], v[16:31]
	v_or_b32_e32 v34, 0xc0, v160
	v_bitop3_b32 v34, v34, v43, v44 bitop3:0xde
	v_add_u32_e32 v176, 0, v34
	s_waitcnt lgkmcnt(0)
; __device__ __forceinline__ void partialSM(f32x16& p0, f32x16& p1, float& m_reg, float& mn, float& alpha) {
;   constexpr float C = SCALE * 1.4426950408889634f;
;   float pmax = p0[0];
; #pragma unroll
;   for (int r = 1; r < 16; ++r) pmax = fmaxf(pmax, p0[r]);
; #pragma unroll
;   for (int r = 0; r < 16; ++r) pmax = fmaxf(pmax, p1[r]);
;   { auto rr = __builtin_amdgcn_permlane32_swap(__float_as_uint(pmax), __float_as_uint(pmax), false, false);
;     pmax = fmaxf(__uint_as_float(rr[0]), __uint_as_float(rr[1])); }
;   if (__builtin_expect(__all(pmax - m_reg <= THR / SCALE), 1)) { mn = m_reg; alpha = 1.f; }
;   else { mn = fmaxf(m_reg, pmax); alpha = __builtin_amdgcn_exp2f((m_reg - mn) * C); m_reg = mn; }
;   float mnC = -mn * C;
; #pragma unroll
;   for (int r = 0; r < 16; ++r) p0[r] = fmaf(p0[r], C, mnC);
; #pragma unroll
;   for (int r = 0; r < 16; ++r) p1[r] = fmaf(p1[r], C, mnC);
; #pragma unroll
;   for (int r = 0; r < 16; ++r) p0[r] = __builtin_amdgcn_exp2f(p0[r]);
; }
; __device__ __forceinline__ void finishSM(f32x16& p0, f32x16& p1, float alpha, float& l_reg, bf16x8& pa0, bf16x8& pa1, bf16x8& pa2, bf16x8& pa3) {
; #pragma unroll
;   for (int r = 0; r < 16; ++r) p1[r] = __builtin_amdgcn_exp2f(p1[r]);
;   float ps = 0;
; #pragma unroll
;   for (int r = 0; r < 16; ++r) ps += p0[r];
; #pragma unroll
;   for (int r = 0; r < 16; ++r) ps += p1[r];
;   { auto rr = __builtin_amdgcn_permlane32_swap(__float_as_uint(ps), __float_as_uint(ps), false, false);
;     ps = __uint_as_float(rr[0]) + __uint_as_float(rr[1]); }
	v_mfma_f32_32x32x16_bf16 v[0:15], v[38:41], v[104:107], v[0:15]
	ds_read_b128 v[34:37], v176
	ds_read_b128 v[38:41], v176 offset:8192
	s_waitcnt lgkmcnt(1)
	v_mfma_f32_32x32x16_bf16 v[16:31], v[34:37], v[100:103], v[16:31]
	v_or_b32_e32 v34, 0xe0, v160
	v_bitop3_b32 v34, v34, v43, v44 bitop3:0xde
	v_add_u32_e32 v177, 0, v34
	ds_read_b128 v[34:37], v177
	v_lshlrev_b32_e32 v43, 3, v165
	v_and_b32_e32 v44, 0xc0, v46
	s_waitcnt lgkmcnt(1)
	v_mfma_f32_32x32x16_bf16 v[0:15], v[38:41], v[100:103], v[0:15]
	ds_read_b128 v[38:41], v177 offset:8192
	s_waitcnt lgkmcnt(1)
	v_mfma_f32_32x32x16_bf16 v[16:31], v[34:37], v[96:99], v[16:31]
	v_and_b32_e32 v34, 32, v42
	v_and_or_b32 v35, v43, 24, v44
	v_and_b32_e32 v36, 0x100, v43
	v_or3_b32 v166, v35, v34, v36
	v_add_u32_e32 v62, s1, v166
	s_nop 6
	v_max_f32_e32 v34, v17, v17
	v_max_f32_e32 v35, v16, v16
	s_waitcnt lgkmcnt(0)
	v_mfma_f32_32x32x16_bf16 v[0:15], v[38:41], v[96:99], v[0:15]
	v_max_f32_e32 v34, v35, v34
	v_max3_f32 v34, v34, v18, v19
	v_max3_f32 v34, v34, v20, v21
	v_max3_f32 v34, v34, v22, v23
	v_max3_f32 v34, v34, v24, v25
	v_max3_f32 v34, v34, v26, v27
	v_max3_f32 v34, v34, v28, v29
	v_max3_f32 v34, v34, v30, v31
	s_nop 3
	v_max3_f32 v34, v34, v0, v1
	v_max3_f32 v34, v34, v2, v3
	v_max3_f32 v34, v34, v4, v5
	v_max3_f32 v34, v34, v6, v7
	v_max3_f32 v34, v34, v8, v9
	v_max3_f32 v34, v34, v10, v11
	v_max3_f32 v34, v34, v12, v13
	v_max3_f32 v34, v34, v14, v15
	v_mov_b32_e32 v35, v34
	s_nop 1
	v_permlane32_swap_b32_e32 v34, v35
	v_max_f32_e32 v35, v35, v35
	v_max_f32_e32 v34, v34, v34
	v_max_f32_e32 v34, v34, v35
	v_add_f32_e32 v35, 0x7149f2ca, v34
	v_cmp_ge_f32_e32 vcc, s43, v35
	s_cmp_eq_u64 vcc, exec
	v_max_f32_e32 v178, 0xf149f2ca, v34
	s_cselect_b64 s[2:3], -1, 0
	v_cndmask_b32_e64 v179, v178, v162, s[2:3]
	v_mul_f32_e32 v182, 0xbe0293ee, v179
	v_fmamk_f32 v16, v16, 0x3e0293ee, v182
	v_fmamk_f32 v17, v17, 0x3e0293ee, v182
	v_fmamk_f32 v18, v18, 0x3e0293ee, v182
	v_fmamk_f32 v19, v19, 0x3e0293ee, v182
	v_fmamk_f32 v20, v20, 0x3e0293ee, v182
	v_fmamk_f32 v21, v21, 0x3e0293ee, v182
	v_fmamk_f32 v22, v22, 0x3e0293ee, v182
	v_fmamk_f32 v23, v23, 0x3e0293ee, v182
	v_fmamk_f32 v24, v24, 0x3e0293ee, v182
	v_fmamk_f32 v25, v25, 0x3e0293ee, v182
	v_fmamk_f32 v26, v26, 0x3e0293ee, v182
	v_fmamk_f32 v27, v27, 0x3e0293ee, v182
	v_fmamk_f32 v28, v28, 0x3e0293ee, v182
	v_fmamk_f32 v29, v29, 0x3e0293ee, v182
	v_fmamk_f32 v30, v30, 0x3e0293ee, v182
	v_fmamk_f32 v31, v31, 0x3e0293ee, v182
	v_exp_f32_e32 v128, v16
	v_exp_f32_e32 v129, v17
	v_exp_f32_e32 v130, v18
	v_exp_f32_e32 v131, v19
	v_exp_f32_e32 v132, v20
	v_exp_f32_e32 v133, v21
	v_exp_f32_e32 v134, v22
	v_exp_f32_e32 v135, v23
	v_exp_f32_e32 v136, v24
	v_exp_f32_e32 v137, v25
	v_exp_f32_e32 v138, v26
	v_exp_f32_e32 v139, v27
	v_exp_f32_e32 v140, v28
	v_exp_f32_e32 v141, v29
	v_exp_f32_e32 v142, v30
	v_exp_f32_e32 v143, v31
	v_fmamk_f32 v50, v0, 0x3e0293ee, v182
	v_fmamk_f32 v51, v1, 0x3e0293ee, v182
	v_fmamk_f32 v52, v2, 0x3e0293ee, v182
	v_fmamk_f32 v53, v3, 0x3e0293ee, v182
	v_fmamk_f32 v54, v4, 0x3e0293ee, v182
	v_fmamk_f32 v55, v5, 0x3e0293ee, v182
	v_fmamk_f32 v56, v6, 0x3e0293ee, v182
	v_fmamk_f32 v57, v7, 0x3e0293ee, v182
	v_fmamk_f32 v58, v8, 0x3e0293ee, v182
	v_fmamk_f32 v59, v9, 0x3e0293ee, v182
	v_fmamk_f32 v60, v10, 0x3e0293ee, v182
	v_fmamk_f32 v61, v11, 0x3e0293ee, v182
	v_fmamk_f32 v63, v12, 0x3e0293ee, v182
	v_fmamk_f32 v144, v13, 0x3e0293ee, v182
	v_fmamk_f32 v145, v14, 0x3e0293ee, v182
	v_fmamk_f32 v146, v15, 0x3e0293ee, v182
	ds_read_b128 v[0:3], v170 offset:16384
	ds_read_b128 v[4:7], v170 offset:24576
	v_exp_f32_e32 v147, v50
	v_add_f32_e32 v50, 0, v128
	v_add_f32_e32 v50, v129, v50
	s_waitcnt lgkmcnt(1)
	v_mfma_f32_32x32x16_bf16 v[80:95], v[0:3], v[124:127], 0
	v_add_f32_e32 v50, v130, v50
	v_exp_f32_e32 v148, v51
	v_exp_f32_e32 v149, v52
	v_exp_f32_e32 v150, v53
	v_exp_f32_e32 v54, v54
	s_waitcnt lgkmcnt(0)
	v_mfma_f32_32x32x16_bf16 v[64:79], v[4:7], v[124:127], 0
	ds_read_b128 v[0:3], v171 offset:16384
	ds_read_b128 v[4:7], v171 offset:24576
	ds_read_b128 v[8:11], v172 offset:16384
	ds_read_b128 v[12:15], v172 offset:24576
	s_waitcnt lgkmcnt(3)
	v_mfma_f32_32x32x16_bf16 v[80:95], v[0:3], v[116:119], v[80:95]
	ds_read_b128 v[0:3], v173 offset:16384
	ds_read_b128 v[16:19], v173 offset:24576
	ds_read_b128 v[20:23], v174 offset:16384
	ds_read_b128 v[24:27], v174 offset:24576
	ds_read_b128 v[28:31], v175 offset:16384
	ds_read_b128 v[34:37], v175 offset:24576
	ds_read_b128 v[38:41], v176 offset:16384
	ds_read_b128 v[42:45], v176 offset:24576
	s_waitcnt lgkmcnt(10)
	v_mfma_f32_32x32x16_bf16 v[64:79], v[4:7], v[116:119], v[64:79]
	ds_read_b128 v[4:7], v177 offset:16384
	ds_read_b128 v[46:49], v177 offset:24576
	s_waitcnt lgkmcnt(11)
	v_mfma_f32_32x32x16_bf16 v[80:95], v[8:11], v[120:123], v[80:95]
	v_exp_f32_e32 v8, v55
	v_exp_f32_e32 v9, v56
	v_exp_f32_e32 v10, v57
	v_exp_f32_e32 v11, v58
	v_exp_f32_e32 v55, v59
	v_exp_f32_e32 v56, v60
	v_exp_f32_e32 v57, v61
	s_waitcnt lgkmcnt(10)
	v_mfma_f32_32x32x16_bf16 v[64:79], v[12:15], v[120:123], v[64:79]
	v_exp_f32_e32 v12, v63
	v_exp_f32_e32 v13, v144
	v_exp_f32_e32 v14, v145
	v_exp_f32_e32 v15, v146
	s_waitcnt lgkmcnt(9)
	v_mfma_f32_32x32x16_bf16 v[80:95], v[0:3], v[112:115], v[80:95]
	v_add_f32_e32 v0, v131, v50
	v_add_f32_e32 v0, v132, v0
	v_add_f32_e32 v0, v133, v0
	v_add_f32_e32 v0, v134, v0
	v_add_f32_e32 v0, v135, v0
	v_add_f32_e32 v0, v136, v0
	v_add_f32_e32 v0, v137, v0
	s_waitcnt lgkmcnt(8)
	v_mfma_f32_32x32x16_bf16 v[64:79], v[16:19], v[112:115], v[64:79]
	v_add_f32_e32 v0, v138, v0
	v_add_f32_e32 v0, v139, v0
	v_add_f32_e32 v0, v140, v0
	v_add_f32_e32 v0, v141, v0
	v_add_f32_e32 v0, v142, v0
	v_add_f32_e32 v0, v143, v0
	v_add_f32_e32 v0, v147, v0
	s_waitcnt lgkmcnt(7)
; #define SBAR() __builtin_amdgcn_sched_barrier(0)
; __device__ __forceinline__ void finishSM(f32x16& p0, f32x16& p1, float alpha, float& l_reg, bf16x8& pa0, bf16x8& pa1, bf16x8& pa2, bf16x8& pa3) {
;     ...
;   PK4(p0, 0, pa0); PK4(p0, 8, pa1); PK4(p1, 0, pa2); PK4(p1, 8, pa3);
;     ...
; }
; __device__ __forceinline__ void qkt(f32x16& p0, f32x16& p1, const bf16* Ks, const bf16x8* qr, int r32, int hi) {
;   p0 = f32x16{}; p1 = f32x16{};
; #pragma unroll
;   for (int d0 = 0; d0 < 8; ++d0) { int cb = (d0 * 16 + hi * 8) * 2;
;     bf16x8 b0 = *reinterpret_cast<const bf16x8*>((const char*)Ks + KSWZ(r32, cb));
;     bf16x8 b1 = *reinterpret_cast<const bf16x8*>((const char*)Ks + KSWZ(32 + r32, cb));
;     p0 = __builtin_amdgcn_mfma_f32_32x32x16_bf16(b0, qr[d0], p0, 0, 0, 0);
;     p1 = __builtin_amdgcn_mfma_f32_32x32x16_bf16(b1, qr[d0], p1, 0, 0, 0); }
; }
; __device__ __forceinline__ int v_st(int k, int c) { const int kk = (k & ~0xC) | ((k & 4) << 1) | ((k & 8) >> 1); return ((kk >> 3) * 4 + (c >> 5)) * 512 + ((kk & 7) * 32 + (c & 31)) * 2; }
; __device__ __forceinline__ int v_rd_base(int lane) { return ((lane & 3) << 3) | (((lane >> 2) & 3) << 6) | (((lane >> 4) & 1) << 5) | (((lane >> 5) & 1) << 8); }
; template <int OFF> __device__ __forceinline__ s16x4 tr_read(int vb) {
;   s16x4 r; asm volatile("ds_read_b64_tr_b16 %0, %1 offset:%2" : "=&v"(r) : "v"(vb), "i"(OFF) : "memory"); return r;
; }
; template <int D0> __device__ __forceinline__ void pv_one(f32x16& od, int vb, bf16x8 pa0, bf16x8 pa1, bf16x8 pa2, bf16x8 pa3) {
;   const s16x4 l0 = tr_read<v_rd_off(D0, 0, 0)>(vb), h0 = tr_read<v_rd_off(D0, 0, 1)>(vb), l1 = tr_read<v_rd_off(D0, 1, 0)>(vb), h1 = tr_read<v_rd_off(D0, 1, 1)>(vb);
;   const s16x4 l2 = tr_read<v_rd_off(D0, 2, 0)>(vb), h2 = tr_read<v_rd_off(D0, 2, 1)>(vb), l3 = tr_read<v_rd_off(D0, 3, 0)>(vb), h3 = tr_read<v_rd_off(D0, 3, 1)>(vb);
;   asm volatile("s_waitcnt lgkmcnt(0)" ::: "memory"); SBAR();
;     ...
;   od = __builtin_amdgcn_mfma_f32_32x32x16_bf16(pa0, PK(l0, h0), od, 0, 0, 0);
;   od = __builtin_amdgcn_mfma_f32_32x32x16_bf16(pa1, PK(l1, h1), od, 0, 0, 0);
;   od = __builtin_amdgcn_mfma_f32_32x32x16_bf16(pa2, PK(l2, h2), od, 0, 0, 0);
;   od = __builtin_amdgcn_mfma_f32_32x32x16_bf16(pa3, PK(l3, h3), od, 0, 0, 0);
;     ...
; }
; __device__ __forceinline__ void pv_d0(f32x16* o, int vb, bf16x8 pa0, bf16x8 pa1, bf16x8 pa2, bf16x8 pa3) {
	v_mfma_f32_32x32x16_bf16 v[80:95], v[20:23], v[108:111], v[80:95]
	v_add_f32_e32 v0, v148, v0
	v_add_f32_e32 v0, v149, v0
	v_add_f32_e32 v0, v150, v0
	v_add_f32_e32 v0, v54, v0
	v_add_f32_e32 v0, v8, v0
	v_add_f32_e32 v0, v9, v0
	v_add_f32_e32 v0, v10, v0
	s_waitcnt lgkmcnt(6)
	v_mfma_f32_32x32x16_bf16 v[64:79], v[24:27], v[108:111], v[64:79]
	v_add_f32_e32 v0, v11, v0
	v_add_f32_e32 v0, v55, v0
	v_add_f32_e32 v0, v56, v0
	v_add_f32_e32 v0, v57, v0
	v_add_f32_e32 v0, v12, v0
	v_add_f32_e32 v0, v13, v0
	v_add_f32_e32 v0, v14, v0
	s_waitcnt lgkmcnt(5)
	v_mfma_f32_32x32x16_bf16 v[80:95], v[28:31], v[104:107], v[80:95]
	v_add_f32_e32 v167, v15, v0
	v_mov_b32_e32 v168, v167
	v_cvt_pk_bf16_f32 v50, v128, v129
	v_cvt_pk_bf16_f32 v51, v130, v131
	v_cvt_pk_bf16_f32 v52, v132, v133
	v_cvt_pk_bf16_f32 v53, v134, v135
	s_nop 1
	v_permlane32_swap_b32_e32 v167, v168
	s_waitcnt lgkmcnt(4)
	v_mfma_f32_32x32x16_bf16 v[64:79], v[34:37], v[104:107], v[64:79]
	v_permlane32_swap_b32_e32 v50, v52
	v_permlane32_swap_b32_e32 v51, v53
	v_cvt_pk_bf16_f32 v184, v136, v137
	v_cvt_pk_bf16_f32 v185, v138, v139
	v_cvt_pk_bf16_f32 v186, v140, v141
	s_waitcnt lgkmcnt(3)
	v_mfma_f32_32x32x16_bf16 v[80:95], v[38:41], v[100:103], v[80:95]
	v_cvt_pk_bf16_f32 v187, v142, v143
	v_cvt_pk_bf16_f32 v188, v147, v148
	v_cvt_pk_bf16_f32 v189, v149, v150
	v_cvt_pk_bf16_f32 v190, v54, v8
	v_cvt_pk_bf16_f32 v191, v9, v10
	v_cvt_pk_bf16_f32 v192, v11, v55
	v_cvt_pk_bf16_f32 v193, v56, v57
	s_waitcnt lgkmcnt(2)
	v_mfma_f32_32x32x16_bf16 v[64:79], v[42:45], v[100:103], v[64:79]
	v_cvt_pk_bf16_f32 v194, v12, v13
	v_cvt_pk_bf16_f32 v195, v14, v15
	v_permlane32_swap_b32_e32 v184, v186
	v_permlane32_swap_b32_e32 v185, v187
	v_permlane32_swap_b32_e32 v188, v190
	s_waitcnt lgkmcnt(1)
	v_mfma_f32_32x32x16_bf16 v[80:95], v[4:7], v[96:99], v[80:95]
	v_permlane32_swap_b32_e32 v189, v191
	v_permlane32_swap_b32_e32 v192, v194
	v_permlane32_swap_b32_e32 v193, v195
	s_waitcnt lgkmcnt(0)
	v_mfma_f32_32x32x16_bf16 v[64:79], v[46:49], v[96:99], v[64:79]
	v_add_co_u32_e32 v0, vcc, s44, v32
	s_nop 1
	v_addc_co_u32_e32 v1, vcc, 0, v33, vcc
	v_add_co_u32_e32 v2, vcc, s45, v32
	s_nop 1
	v_addc_co_u32_e32 v3, vcc, 0, v33, vcc
	v_add_co_u32_e32 v4, vcc, s46, v32
	s_nop 1
	v_addc_co_u32_e32 v5, vcc, 0, v33, vcc
	v_add_co_u32_e32 v6, vcc, s47, v32
	s_nop 1
	v_addc_co_u32_e32 v7, vcc, 0, v33, vcc
	global_load_dwordx4 v[132:135], v[0:1], off offset:1024
	global_load_dwordx4 v[128:131], v[0:1], off
	global_load_dwordx4 v[144:147], v[2:3], off offset:1024
	global_load_dwordx4 v[136:139], v[2:3], off
	global_load_dwordx4 v[152:155], v[4:5], off offset:1024
	global_load_dwordx4 v[140:143], v[4:5], off
	global_load_dwordx4 v[156:159], v[6:7], off offset:1024
	global_load_dwordx4 v[148:151], v[6:7], off
	ds_read_b64_tr_b16 v[0:1], v62 offset:0
	ds_read_b64_tr_b16 v[2:3], v62 offset:0x800
	ds_read_b64_tr_b16 v[16:17], v62 offset:0x1000
	ds_read_b64_tr_b16 v[18:19], v62 offset:0x1800
	ds_read_b64_tr_b16 v[20:21], v62 offset:0x2000
	ds_read_b64_tr_b16 v[22:23], v62 offset:0x2800
	ds_read_b64_tr_b16 v[24:25], v62 offset:0x3000
	ds_read_b64_tr_b16 v[26:27], v62 offset:0x3800
	s_waitcnt lgkmcnt(0)
	s_nop 0
	v_mfma_f32_32x32x16_bf16 v[0:15], v[50:53], v[0:3], 0
	v_mfma_f32_32x32x16_bf16 v[0:15], v[184:187], v[16:19], v[0:15]
	ds_read_b64_tr_b16 v[16:17], v62 offset:0x200
	ds_read_b64_tr_b16 v[18:19], v62 offset:0xa00
	ds_read_b64_tr_b16 v[32:33], v62 offset:0x1200
	ds_read_b64_tr_b16 v[34:35], v62 offset:0x1a00
	ds_read_b64_tr_b16 v[36:37], v62 offset:0x2200
	ds_read_b64_tr_b16 v[38:39], v62 offset:0x2a00
	ds_read_b64_tr_b16 v[40:41], v62 offset:0x3200
	v_mfma_f32_32x32x16_bf16 v[0:15], v[188:191], v[20:23], v[0:15]
	ds_read_b64_tr_b16 v[42:43], v62 offset:0x3a00
	s_waitcnt lgkmcnt(0)
	v_mfma_f32_32x32x16_bf16 v[0:15], v[192:195], v[24:27], v[0:15]
	v_mfma_f32_32x32x16_bf16 v[16:31], v[50:53], v[16:19], 0
	v_mfma_f32_32x32x16_bf16 v[16:31], v[184:187], v[32:35], v[16:31]
	ds_read_b64_tr_b16 v[32:33], v62 offset:0x400
	ds_read_b64_tr_b16 v[34:35], v62 offset:0xc00
	ds_read_b64_tr_b16 v[54:55], v62 offset:0x1400
	ds_read_b64_tr_b16 v[56:57], v62 offset:0x1c00
	ds_read_b64_tr_b16 v[58:59], v62 offset:0x2400
	ds_read_b64_tr_b16 v[60:61], v62 offset:0x2c00
	ds_read_b64_tr_b16 v[196:197], v62 offset:0x3400
	v_mfma_f32_32x32x16_bf16 v[16:31], v[188:191], v[36:39], v[16:31]
	ds_read_b64_tr_b16 v[198:199], v62 offset:0x3c00
	s_waitcnt lgkmcnt(0)
	v_mfma_f32_32x32x16_bf16 v[16:31], v[192:195], v[40:43], v[16:31]
	v_mfma_f32_32x32x16_bf16 v[32:47], v[50:53], v[32:35], 0
	v_mfma_f32_32x32x16_bf16 v[32:47], v[184:187], v[54:57], v[32:47]
	ds_read_b64_tr_b16 v[54:55], v62 offset:0x600
	ds_read_b64_tr_b16 v[56:57], v62 offset:0xe00
	ds_read_b64_tr_b16 v[200:201], v62 offset:0x1600
	ds_read_b64_tr_b16 v[202:203], v62 offset:0x1e00
	ds_read_b64_tr_b16 v[204:205], v62 offset:0x2600
	ds_read_b64_tr_b16 v[206:207], v62 offset:0x2e00
	ds_read_b64_tr_b16 v[208:209], v62 offset:0x3600
	v_mfma_f32_32x32x16_bf16 v[32:47], v[188:191], v[58:61], v[32:47]
	ds_read_b64_tr_b16 v[210:211], v62 offset:0x3e00
	s_waitcnt lgkmcnt(0)
	v_mfma_f32_32x32x16_bf16 v[32:47], v[192:195], v[196:199], v[32:47]
	v_max_f32_e32 v48, v81, v81
	v_max_f32_e32 v49, v80, v80
	v_max_f32_e32 v48, v49, v48
	v_max3_f32 v48, v48, v82, v83
	v_max3_f32 v169, v48, v84, v85
	v_mfma_f32_32x32x16_bf16 v[48:63], v[50:53], v[54:57], 0
	v_max3_f32 v169, v169, v86, v87
	v_max3_f32 v169, v169, v88, v89
	v_max3_f32 v169, v169, v90, v91
	v_max3_f32 v169, v169, v92, v93
	v_max3_f32 v169, v169, v94, v95
	v_max3_f32 v169, v169, v64, v65
	v_max3_f32 v169, v169, v66, v67
	v_mfma_f32_32x32x16_bf16 v[48:63], v[184:187], v[200:203], v[48:63]
	v_max3_f32 v169, v169, v68, v69
	v_max3_f32 v169, v169, v70, v71
	v_max3_f32 v169, v169, v72, v73
	v_max3_f32 v169, v169, v74, v75
	v_max3_f32 v169, v169, v76, v77
	v_max3_f32 v169, v169, v78, v79
	v_mov_b32_e32 v183, v169
	v_mfma_f32_32x32x16_bf16 v[48:63], v[188:191], v[204:207], v[48:63]
	s_nop 0
	v_permlane32_swap_b32_e32 v169, v183
	v_max_f32_e32 v183, v183, v183
	v_max_f32_e32 v169, v169, v169
	v_max_f32_e32 v183, v169, v183
	v_sub_f32_e32 v169, v183, v179
	v_cmp_ge_f32_e32 vcc, s43, v169
	v_mfma_f32_32x32x16_bf16 v[48:63], v[192:195], v[208:211], v[48:63]
	s_cmp_eq_u64 vcc, exec
	v_mov_b32_e32 v169, 1.0
	s_cbranch_scc0 .LBB0_858
